# v16: like v15 with 5632 items offloaded
# speedup vs baseline: 1.0475x; 1.0014x over previous
; __device__ __forceinline__ void phase_prologue(PtrTab TB, unsigned char* ws, float* xout, int l, LAS unsigned char* lds, int gw, int NGW, int lane, int wave) {
;     ...
;     for (int it = gw; it < S14; it += NGW) {
.LBB0_23:
	s_cmpk_eq_u32 s8, 0x800
	s_cbranch_scc0 .Ltr_start
	s_cmpk_eq_u32 s94, 1
	s_cbranch_scc0 .Ltr_start
	s_cmpk_lt_u32 s71, 0x1600
	s_cbranch_scc0 .Ltr_start
	s_addk_i32 s71, 0x1600

; #define LAS __attribute__((address_space(3)))
; __device__ __forceinline__ void tr_item(const float* W, int ldn, int col0, int k0, const float* g, bf16* WT, int ldk, int drow0, LAS float* scr, int lane) {
;     ...
;     for (int i = 0; i < 16; ++i) { const int kk = 4 * i + kr; f32x4 v = *(const f32x4*)(W + (size_t)(k0 + kk) * ldn + col0 + n4); if (g) v = v * g[k0 + kk];
;         LAS float* d = scr + kk * 65 + n4; d[0] = v.x; d[1] = v.y; d[2] = v.z; d[3] = v.w; }
.Lofl_gdone:
	global_load_dwordx4 v[146:149], v232, s[2:3] nt
	v_add_u32_e32 v232, s38, v232
	global_load_dwordx4 v[150:153], v232, s[2:3] nt
	v_add_u32_e32 v232, s38, v232
	global_load_dwordx4 v[154:157], v232, s[2:3] nt
	v_add_u32_e32 v232, s38, v232
	global_load_dwordx4 v[158:161], v232, s[2:3] nt
	v_add_u32_e32 v232, s38, v232
	global_load_dwordx4 v[166:169], v232, s[2:3] nt
	v_add_u32_e32 v232, s38, v232
	global_load_dwordx4 v[170:173], v232, s[2:3] nt
	v_add_u32_e32 v232, s38, v232
	global_load_dwordx4 v[174:177], v232, s[2:3] nt
	v_add_u32_e32 v232, s38, v232
	global_load_dwordx4 v[178:181], v232, s[2:3] nt
	v_add_u32_e32 v232, s38, v232
	global_load_dwordx4 v[182:185], v232, s[2:3] nt
	v_add_u32_e32 v232, s38, v232
	global_load_dwordx4 v[186:189], v232, s[2:3] nt
	v_add_u32_e32 v232, s38, v232
	global_load_dwordx4 v[190:193], v232, s[2:3] nt
	v_add_u32_e32 v232, s38, v232
	global_load_dwordx4 v[108:111], v232, s[2:3] nt
	v_add_u32_e32 v232, s38, v232
	global_load_dwordx4 v[112:115], v232, s[2:3] nt
	v_add_u32_e32 v232, s38, v232
	global_load_dwordx4 v[116:119], v232, s[2:3] nt
	v_add_u32_e32 v232, s38, v232
	global_load_dwordx4 v[120:123], v232, s[2:3] nt
	v_add_u32_e32 v232, s38, v232
	global_load_dwordx4 v[124:127], v232, s[2:3] nt
	s_waitcnt vmcnt(15)
	v_mul_f32_e32 v146, v210, v146
	v_mul_f32_e32 v147, v210, v147
	v_mul_f32_e32 v148, v210, v148
	v_mul_f32_e32 v149, v210, v149
	ds_write2_b32 v242, v146, v147 offset1:1
	ds_write2_b32 v242, v148, v149 offset0:2 offset1:3
	v_add_u32_e32 v242, 0x410, v242
	s_waitcnt vmcnt(14)
	v_mul_f32_e32 v150, v211, v150
	v_mul_f32_e32 v151, v211, v151
	v_mul_f32_e32 v152, v211, v152
	v_mul_f32_e32 v153, v211, v153
	ds_write2_b32 v242, v150, v151 offset1:1
	ds_write2_b32 v242, v152, v153 offset0:2 offset1:3
	v_add_u32_e32 v242, 0x410, v242
	s_waitcnt vmcnt(13)
	v_mul_f32_e32 v154, v212, v154
	v_mul_f32_e32 v155, v212, v155
	v_mul_f32_e32 v156, v212, v156
	v_mul_f32_e32 v157, v212, v157
	ds_write2_b32 v242, v154, v155 offset1:1
	ds_write2_b32 v242, v156, v157 offset0:2 offset1:3
	v_add_u32_e32 v242, 0x410, v242
	s_waitcnt vmcnt(12)
	v_mul_f32_e32 v158, v213, v158
	v_mul_f32_e32 v159, v213, v159
	v_mul_f32_e32 v160, v213, v160
	v_mul_f32_e32 v161, v213, v161
	ds_write2_b32 v242, v158, v159 offset1:1
	ds_write2_b32 v242, v160, v161 offset0:2 offset1:3
	v_add_u32_e32 v242, 0x410, v242
	s_waitcnt vmcnt(11)
	v_mul_f32_e32 v166, v214, v166
	v_mul_f32_e32 v167, v214, v167
	v_mul_f32_e32 v168, v214, v168
	v_mul_f32_e32 v169, v214, v169
	ds_write2_b32 v242, v166, v167 offset1:1
	ds_write2_b32 v242, v168, v169 offset0:2 offset1:3
	v_add_u32_e32 v242, 0x410, v242
	s_waitcnt vmcnt(10)
	v_mul_f32_e32 v170, v215, v170
	v_mul_f32_e32 v171, v215, v171
	v_mul_f32_e32 v172, v215, v172
	v_mul_f32_e32 v173, v215, v173
	ds_write2_b32 v242, v170, v171 offset1:1
	ds_write2_b32 v242, v172, v173 offset0:2 offset1:3
	v_add_u32_e32 v242, 0x410, v242
	s_waitcnt vmcnt(9)
	v_mul_f32_e32 v174, v216, v174
	v_mul_f32_e32 v175, v216, v175
	v_mul_f32_e32 v176, v216, v176
	v_mul_f32_e32 v177, v216, v177
	ds_write2_b32 v242, v174, v175 offset1:1
	ds_write2_b32 v242, v176, v177 offset0:2 offset1:3
	v_add_u32_e32 v242, 0x410, v242
	s_waitcnt vmcnt(8)
	v_mul_f32_e32 v178, v217, v178
	v_mul_f32_e32 v179, v217, v179
	v_mul_f32_e32 v180, v217, v180
	v_mul_f32_e32 v181, v217, v181
	ds_write2_b32 v242, v178, v179 offset1:1
	ds_write2_b32 v242, v180, v181 offset0:2 offset1:3
	v_add_u32_e32 v242, 0x410, v242
	s_waitcnt vmcnt(7)
	v_mul_f32_e32 v182, v218, v182
	v_mul_f32_e32 v183, v218, v183
	v_mul_f32_e32 v184, v218, v184
	v_mul_f32_e32 v185, v218, v185
	ds_write2_b32 v242, v182, v183 offset1:1
	ds_write2_b32 v242, v184, v185 offset0:2 offset1:3
	v_add_u32_e32 v242, 0x410, v242
	s_waitcnt vmcnt(6)
	v_mul_f32_e32 v186, v219, v186
	v_mul_f32_e32 v187, v219, v187
	v_mul_f32_e32 v188, v219, v188
	v_mul_f32_e32 v189, v219, v189
	ds_write2_b32 v242, v186, v187 offset1:1
	ds_write2_b32 v242, v188, v189 offset0:2 offset1:3
	v_add_u32_e32 v242, 0x410, v242
	s_waitcnt vmcnt(5)
	v_mul_f32_e32 v190, v220, v190
	v_mul_f32_e32 v191, v220, v191
	v_mul_f32_e32 v192, v220, v192
	v_mul_f32_e32 v193, v220, v193
	ds_write2_b32 v242, v190, v191 offset1:1
	ds_write2_b32 v242, v192, v193 offset0:2 offset1:3
	v_add_u32_e32 v242, 0x410, v242
	s_waitcnt vmcnt(4)
	v_mul_f32_e32 v108, v221, v108
	v_mul_f32_e32 v109, v221, v109
	v_mul_f32_e32 v110, v221, v110
	v_mul_f32_e32 v111, v221, v111
	ds_write2_b32 v242, v108, v109 offset1:1
	ds_write2_b32 v242, v110, v111 offset0:2 offset1:3
	v_add_u32_e32 v242, 0x410, v242
	s_waitcnt vmcnt(3)
; #define LAS __attribute__((address_space(3)))
; __device__ __forceinline__ unsigned pk2(float lo, float hi) { return f2bf(lo) | (f2bf(hi) << 16); }
; #define LDS_WAIT() asm volatile("s_waitcnt lgkmcnt(0)" ::: "memory")
; __device__ __forceinline__ void tr_item(const float* W, int ldn, int col0, int k0, const float* g, bf16* WT, int ldk, int drow0, LAS float* scr, int lane) {
;     ...
;     LDS_WAIT(); asm volatile("" ::: "memory");
;     const int c = lane & 7;
; #pragma unroll
;     for (int j = 0; j < 8; ++j) { const int n = (lane >> 3) + 8 * j; const LAS float* s = scr + (8 * c) * 65 + n;
;         v4u o; o.x = pk2(s[0 * 65], s[1 * 65]); o.y = pk2(s[2 * 65], s[3 * 65]); o.z = pk2(s[4 * 65], s[5 * 65]); o.w = pk2(s[6 * 65], s[7 * 65]);
;         *(v4u*)(WT + (size_t)(drow0 + n) * ldk + k0 + 8 * c) = o; }
	v_mul_f32_e32 v112, v222, v112
	v_mul_f32_e32 v113, v222, v113
	v_mul_f32_e32 v114, v222, v114
	v_mul_f32_e32 v115, v222, v115
	ds_write2_b32 v242, v112, v113 offset1:1
	ds_write2_b32 v242, v114, v115 offset0:2 offset1:3
	v_add_u32_e32 v242, 0x410, v242
	s_waitcnt vmcnt(2)
	v_mul_f32_e32 v116, v223, v116
	v_mul_f32_e32 v117, v223, v117
	v_mul_f32_e32 v118, v223, v118
	v_mul_f32_e32 v119, v223, v119
	ds_write2_b32 v242, v116, v117 offset1:1
	ds_write2_b32 v242, v118, v119 offset0:2 offset1:3
	v_add_u32_e32 v242, 0x410, v242
	s_waitcnt vmcnt(1)
	v_mul_f32_e32 v120, v230, v120
	v_mul_f32_e32 v121, v230, v121
	v_mul_f32_e32 v122, v230, v122
	v_mul_f32_e32 v123, v230, v123
	ds_write2_b32 v242, v120, v121 offset1:1
	ds_write2_b32 v242, v122, v123 offset0:2 offset1:3
	v_add_u32_e32 v242, 0x410, v242
	s_waitcnt vmcnt(0)
	v_mul_f32_e32 v124, v231, v124
	v_mul_f32_e32 v125, v231, v125
	v_mul_f32_e32 v126, v231, v126
	v_mul_f32_e32 v127, v231, v127
	ds_write2_b32 v242, v124, v125 offset1:1
	ds_write2_b32 v242, v126, v127 offset0:2 offset1:3
	s_waitcnt lgkmcnt(0)
	ds_read2_b32 v[146:147], v48 offset0:0 offset1:65
	ds_read2_b32 v[148:149], v48 offset0:130 offset1:195
	ds_read2_b32 v[150:151], v243 offset0:4 offset1:69
	ds_read2_b32 v[152:153], v243 offset0:134 offset1:199
	ds_read2_b32 v[154:155], v48 offset0:8 offset1:73
	ds_read2_b32 v[156:157], v48 offset0:138 offset1:203
	ds_read2_b32 v[158:159], v243 offset0:12 offset1:77
	ds_read2_b32 v[160:161], v243 offset0:142 offset1:207
	ds_read2_b32 v[166:167], v48 offset0:16 offset1:81
	ds_read2_b32 v[168:169], v48 offset0:146 offset1:211
	ds_read2_b32 v[170:171], v243 offset0:20 offset1:85
	ds_read2_b32 v[172:173], v243 offset0:150 offset1:215
	s_waitcnt lgkmcnt(8)
	v_cvt_pk_bf16_f32 v146, v146, v147
	v_cvt_pk_bf16_f32 v147, v148, v149
	v_cvt_pk_bf16_f32 v148, v150, v151
	v_cvt_pk_bf16_f32 v149, v152, v153
	global_store_dwordx4 v244, v[146:149], s[24:25]
	ds_read2_b32 v[174:175], v48 offset0:24 offset1:89
	ds_read2_b32 v[176:177], v48 offset0:154 offset1:219
	ds_read2_b32 v[178:179], v243 offset0:28 offset1:93
	ds_read2_b32 v[180:181], v243 offset0:158 offset1:223
	s_waitcnt lgkmcnt(8)
	v_cvt_pk_bf16_f32 v154, v154, v155
	v_cvt_pk_bf16_f32 v155, v156, v157
	v_cvt_pk_bf16_f32 v156, v158, v159
	v_cvt_pk_bf16_f32 v157, v160, v161
	global_store_dwordx4 v245, v[154:157], s[24:25]
	ds_read2_b32 v[182:183], v48 offset0:32 offset1:97
	ds_read2_b32 v[184:185], v48 offset0:162 offset1:227
	ds_read2_b32 v[186:187], v243 offset0:36 offset1:101
	ds_read2_b32 v[188:189], v243 offset0:166 offset1:231
	s_waitcnt lgkmcnt(8)
	v_cvt_pk_bf16_f32 v166, v166, v167
	v_cvt_pk_bf16_f32 v167, v168, v169
	v_cvt_pk_bf16_f32 v168, v170, v171
	v_cvt_pk_bf16_f32 v169, v172, v173
	global_store_dwordx4 v246, v[166:169], s[24:25]
	ds_read2_b32 v[108:109], v48 offset0:40 offset1:105
	ds_read2_b32 v[110:111], v48 offset0:170 offset1:235
	ds_read2_b32 v[112:113], v243 offset0:44 offset1:109
	ds_read2_b32 v[114:115], v243 offset0:174 offset1:239
	s_waitcnt lgkmcnt(8)
	v_cvt_pk_bf16_f32 v174, v174, v175
	v_cvt_pk_bf16_f32 v175, v176, v177
	v_cvt_pk_bf16_f32 v176, v178, v179
	v_cvt_pk_bf16_f32 v177, v180, v181
	global_store_dwordx4 v247, v[174:177], s[24:25]
	ds_read2_b32 v[116:117], v48 offset0:48 offset1:113
	ds_read2_b32 v[118:119], v48 offset0:178 offset1:243
	ds_read2_b32 v[120:121], v243 offset0:52 offset1:117
	ds_read2_b32 v[122:123], v243 offset0:182 offset1:247
	s_waitcnt lgkmcnt(8)
	v_cvt_pk_bf16_f32 v182, v182, v183
	v_cvt_pk_bf16_f32 v183, v184, v185
	v_cvt_pk_bf16_f32 v184, v186, v187
	v_cvt_pk_bf16_f32 v185, v188, v189
	global_store_dwordx4 v248, v[182:185], s[24:25]
	ds_read2_b32 v[124:125], v48 offset0:56 offset1:121
	ds_read2_b32 v[126:127], v48 offset0:186 offset1:251
	ds_read2_b32 v[128:129], v243 offset0:60 offset1:125
	ds_read2_b32 v[130:131], v243 offset0:190 offset1:255
	s_waitcnt lgkmcnt(8)
	v_cvt_pk_bf16_f32 v108, v108, v109
	v_cvt_pk_bf16_f32 v109, v110, v111
	v_cvt_pk_bf16_f32 v110, v112, v113
	v_cvt_pk_bf16_f32 v111, v114, v115
	global_store_dwordx4 v249, v[108:111], s[24:25]
	s_waitcnt lgkmcnt(4)
	v_cvt_pk_bf16_f32 v116, v116, v117
	v_cvt_pk_bf16_f32 v117, v118, v119
	v_cvt_pk_bf16_f32 v118, v120, v121
	v_cvt_pk_bf16_f32 v119, v122, v123
	global_store_dwordx4 v250, v[116:119], s[24:25]
	s_waitcnt lgkmcnt(0)
	v_cvt_pk_bf16_f32 v124, v124, v125
	v_cvt_pk_bf16_f32 v125, v126, v127
	v_cvt_pk_bf16_f32 v126, v128, v129
	v_cvt_pk_bf16_f32 v127, v130, v131
	global_store_dwordx4 v251, v[124:127], s[24:25]
	s_addk_i32 s10, 0x400
	s_cmpk_lt_u32 s10, 0x1600
	s_cbranch_scc1 .Lofl_item
